# P0: p->bf16 loads issued first thing in P0 (held in v186-221 across the transposes and x pass); (c) only converts and stores
# speedup vs baseline: 1.0011x; 1.0011x over previous
.LBB0_5:
	s_or_b64 exec, exec, s[2:3]
	s_cmpk_lg_i32 s58, 0x100
	s_cbranch_scc1 .Lp0pre_skip
	s_load_dwordx4 s[96:99], s[0:1], 0x10
	v_lshl_add_u32 v222, s59, 9, v0
	v_lshlrev_b32_e32 v222, 4, v222
	s_waitcnt lgkmcnt(0)
	s_cmp_lt_u32 s59, 64
	s_cbranch_scc0 .Lp0pre_no8
	global_load_dwordx4 v[218:221], v222, s[98:99]
.Lp0pre_no8:
	global_load_dwordx4 v[186:189], v222, s[96:97]
	s_add_u32 s96, s96, 0x200000
	s_addc_u32 s97, s97, 0
	global_load_dwordx4 v[190:193], v222, s[96:97]
	s_add_u32 s96, s96, 0x200000
	s_addc_u32 s97, s97, 0
	global_load_dwordx4 v[194:197], v222, s[96:97]
	s_add_u32 s96, s96, 0x200000
	s_addc_u32 s97, s97, 0
	global_load_dwordx4 v[198:201], v222, s[96:97]
	s_add_u32 s96, s96, 0x200000
	s_addc_u32 s97, s97, 0
	global_load_dwordx4 v[202:205], v222, s[96:97]
	s_add_u32 s96, s96, 0x200000
	s_addc_u32 s97, s97, 0
	global_load_dwordx4 v[206:209], v222, s[96:97]
	s_add_u32 s96, s96, 0x200000
	s_addc_u32 s97, s97, 0
	global_load_dwordx4 v[210:213], v222, s[96:97]
	s_add_u32 s96, s96, 0x200000
	s_addc_u32 s97, s97, 0
	global_load_dwordx4 v[214:217], v222, s[96:97]
.Lp0pre_skip:
	s_load_dwordx16 s[60:75], s[0:1], 0xc0
	v_mov_b32_e32 v128, v0
	s_movk_i32 s2, 0x1180
	v_ashrrev_i32_e32 v129, 6, v128
	s_add_u32 s97, s59, 0x80
	s_and_b32 s97, s97, 0xff
	s_cmpk_lg_i32 s58, 0x100
	s_cselect_b32 s97, s59, s97
	v_lshl_add_u32 v1, s97, 3, v129
	v_and_b32_e32 v130, 63, v128
	v_cmp_gt_i32_e32 vcc, s2, v1
	v_lshlrev_b32_e32 v83, 2, v128
	s_and_saveexec_b64 s[2:3], vcc
	s_cbranch_execz .LBB0_38
	s_movk_i32 s4, 0x2100
	v_mul_lo_u32 v2, v129, s4
	v_lshrrev_b32_e32 v56, 5, v130
	v_add_u32_e32 v8, 0, v2
	v_mul_u32_u24_e32 v2, 0x84, v56
	v_and_b32_e32 v22, 0x7c, v83
	v_add3_u32 v57, v8, v2, v22
	v_lshlrev_b32_e32 v2, 3, v130
	v_and_b32_e32 v2, 56, v2
	s_load_dwordx16 s[36:51], s[0:1], 0x40
	v_lshrrev_b32_e32 v58, 3, v130
	v_mul_u32_u24_e32 v9, 0x84, v2
	v_lshlrev_b32_e32 v2, 1, v2
	v_mov_b32_e32 v3, 0
	v_lshl_add_u64 v[4:5], s[76:77], 0, v[2:3]
	s_mov_b64 s[4:5], 0x1100000
	v_lshlrev_b32_e32 v2, 2, v58
	v_lshl_add_u64 v[6:7], v[4:5], 0, s[4:5]
	v_add3_u32 v59, v8, v9, v2
	s_mov_b64 s[4:5], 0xf00000
	s_lshl_b32 s18, s58, 3
	v_lshlrev_b32_e32 v2, 3, v129
	v_lshl_add_u64 v[8:9], v[4:5], 0, s[4:5]
	s_mov_b64 s[4:5], 0xd00000
	s_waitcnt lgkmcnt(0)
	s_cmp_lg_u64 s[66:67], 0
	v_lshl_add_u32 v63, s97, 6, v2
	v_lshlrev_b32_e32 v2, 1, v129
	v_lshl_add_u64 v[10:11], v[4:5], 0, s[4:5]
	s_mov_b64 s[4:5], 0x900000
	v_mov_b32_e32 v23, v3
	s_cselect_b64 s[6:7], -1, 0
	s_cmp_lg_u64 s[38:39], 0
	v_lshl_add_u32 v64, s97, 4, v2
	v_lshlrev_b32_e32 v2, 6, v129
	v_or_b32_e32 v60, 8, v58
	v_or_b32_e32 v61, 16, v58
	v_or_b32_e32 v62, 24, v58
	v_lshl_add_u64 v[12:13], v[4:5], 0, s[4:5]
	v_lshl_add_u64 v[14:15], s[70:71], 0, v[22:23]
	v_lshl_add_u64 v[16:17], s[68:69], 0, v[22:23]
	v_lshl_add_u64 v[18:19], s[60:61], 0, v[22:23]
	v_lshl_add_u64 v[20:21], s[64:65], 0, v[22:23]
	v_lshl_add_u64 v[22:23], s[36:37], 0, v[22:23]
	s_mov_b64 s[4:5], 0
	s_cselect_b64 s[8:9], -1, 0
	s_lshl_b32 s19, s58, 6
	s_lshl_b32 s20, s58, 4
	v_lshl_add_u32 v65, s97, 9, v2
	s_lshl_b32 s21, s58, 9
	s_movk_i32 s22, 0x8ff
	s_movk_i32 s23, 0xcff
	s_movk_i32 s24, 0xeff
	s_movk_i32 s25, 0x10ff
	s_mov_b32 s26, 0x12000
	s_movk_i32 s27, 0x3ff
	s_movk_i32 s28, 0x7ff
	s_movk_i32 s29, 0xdff
	s_movk_i32 s30, 0x117f
	v_add_u32_e32 v66, 0x400, v57
	v_add_u32_e32 v67, 0x800, v57
	v_add_u32_e32 v68, 0xc00, v57
	v_add_u32_e32 v69, 0x1000, v57
	v_add_u32_e32 v70, 0x1400, v57
	v_add_u32_e32 v71, 0x1800, v57
	v_add_u32_e32 v72, 0x1c00, v57
	s_branch .LBB0_9

.LBB0_48:
	s_add_u32 s0, s76, 0x3280000
	s_addc_u32 s1, s77, 0
	s_lshl_b32 s33, s59, 9
	s_waitcnt vmcnt(11)
	v_add_u32_e32 v8, s33, v128
	s_cmpk_lg_i32 s58, 0x100
	s_cbranch_scc1 .Lp0c_orig
	v_readlane_b32 s20, v242, 25
	v_readlane_b32 s21, v242, 26
	v_readlane_b32 s22, v242, 27
	v_readlane_b32 s23, v242, 28
	v_lshlrev_b32_e32 v9, 4, v8
	v_lshlrev_b32_e32 v7, 3, v8
	s_mov_b64 s[6:7], s[0:1]
	s_add_u32 s8, s0, 0x800000
	s_addc_u32 s9, s1, 0
	s_nop 1
	s_cmp_lt_u32 s59, 64
	s_cbranch_scc0 .Lp0c_no8b
	v_cvt_pk_bf16_f32 v218, v218, v219
	v_cvt_pk_bf16_f32 v219, v220, v221
	global_store_dwordx2 v7, v[218:219], s[8:9]
.Lp0c_no8b:
	v_cvt_pk_bf16_f32 v186, v186, v187
	v_cvt_pk_bf16_f32 v187, v188, v189
	global_store_dwordx2 v7, v[186:187], s[6:7]
	s_add_u32 s6, s6, 0x100000
	s_addc_u32 s7, s7, 0
	v_cvt_pk_bf16_f32 v190, v190, v191
	v_cvt_pk_bf16_f32 v191, v192, v193
	global_store_dwordx2 v7, v[190:191], s[6:7]
	s_add_u32 s6, s6, 0x100000
	s_addc_u32 s7, s7, 0
	v_cvt_pk_bf16_f32 v194, v194, v195
	v_cvt_pk_bf16_f32 v195, v196, v197
	global_store_dwordx2 v7, v[194:195], s[6:7]
	s_add_u32 s6, s6, 0x100000
	s_addc_u32 s7, s7, 0
	v_cvt_pk_bf16_f32 v198, v198, v199
	v_cvt_pk_bf16_f32 v199, v200, v201
	global_store_dwordx2 v7, v[198:199], s[6:7]
	s_add_u32 s6, s6, 0x100000
	s_addc_u32 s7, s7, 0
	v_cvt_pk_bf16_f32 v202, v202, v203
	v_cvt_pk_bf16_f32 v203, v204, v205
	global_store_dwordx2 v7, v[202:203], s[6:7]
	s_add_u32 s6, s6, 0x100000
	s_addc_u32 s7, s7, 0
	v_cvt_pk_bf16_f32 v206, v206, v207
	v_cvt_pk_bf16_f32 v207, v208, v209
	global_store_dwordx2 v7, v[206:207], s[6:7]
	s_add_u32 s6, s6, 0x100000
	s_addc_u32 s7, s7, 0
	v_cvt_pk_bf16_f32 v210, v210, v211
	v_cvt_pk_bf16_f32 v211, v212, v213
	global_store_dwordx2 v7, v[210:211], s[6:7]
	s_add_u32 s6, s6, 0x100000
	s_addc_u32 s7, s7, 0
	v_cvt_pk_bf16_f32 v214, v214, v215
	v_cvt_pk_bf16_f32 v215, v216, v217
	global_store_dwordx2 v7, v[214:215], s[6:7]
	s_branch .Lp0c_done

	.amdhsa_kernel _Z9hymba_fwd6Params
		.amdhsa_group_segment_fixed_size 0
		.amdhsa_private_segment_fixed_size 0
		.amdhsa_kernarg_size 520
		.amdhsa_user_sgpr_count 2
		.amdhsa_user_sgpr_dispatch_ptr 0
		.amdhsa_user_sgpr_queue_ptr 0
		.amdhsa_user_sgpr_kernarg_segment_ptr 1
		.amdhsa_user_sgpr_dispatch_id 0
		.amdhsa_user_sgpr_kernarg_preload_length 0
		.amdhsa_user_sgpr_kernarg_preload_offset 0
		.amdhsa_user_sgpr_private_segment_size 0
		.amdhsa_uses_dynamic_stack 0
		.amdhsa_enable_private_segment 0
		.amdhsa_system_sgpr_workgroup_id_x 1
		.amdhsa_system_sgpr_workgroup_id_y 0
		.amdhsa_system_sgpr_workgroup_id_z 0
		.amdhsa_system_sgpr_workgroup_info 0
		.amdhsa_system_vgpr_workitem_id 0
		.amdhsa_next_free_vgpr 256
		.amdhsa_next_free_sgpr 100
		.amdhsa_accum_offset 256
		.amdhsa_reserve_vcc 1
		.amdhsa_float_round_mode_32 0
		.amdhsa_float_round_mode_16_64 0
		.amdhsa_float_denorm_mode_32 3
		.amdhsa_float_denorm_mode_16_64 3
		.amdhsa_dx10_clamp 1
		.amdhsa_ieee_mode 1
		.amdhsa_fp16_overflow 0
		.amdhsa_tg_split 0
		.amdhsa_exception_fp_ieee_invalid_op 0
		.amdhsa_exception_fp_denorm_src 0
		.amdhsa_exception_fp_ieee_div_zero 0
		.amdhsa_exception_fp_ieee_overflow 0
		.amdhsa_exception_fp_ieee_underflow 0
		.amdhsa_exception_fp_ieee_inexact 0
		.amdhsa_exception_int_div_zero 0
	.end_amdhsa_kernel

.Lfunc_end0:
	.size	_Z9hymba_fwd6Params, .Lfunc_end0-_Z9hymba_fwd6Params
	.set _Z9hymba_fwd6Params.num_vgpr, 256
	.set _Z9hymba_fwd6Params.num_agpr, 0
	.set _Z9hymba_fwd6Params.numbered_sgpr, 100
	.set _Z9hymba_fwd6Params.num_named_barrier, 0
	.set _Z9hymba_fwd6Params.private_seg_size, 0
	.set _Z9hymba_fwd6Params.uses_vcc, 1
	.set _Z9hymba_fwd6Params.uses_flat_scratch, 0
	.set _Z9hymba_fwd6Params.has_dyn_sized_stack, 0
	.set _Z9hymba_fwd6Params.has_recursion, 0
	.set _Z9hymba_fwd6Params.has_indirect_call, 0

amdhsa.kernels:
  - .agpr_count:     0
    .args:
      - .offset:         0
        .size:           264
        .value_kind:     by_value
      - .offset:         264
        .size:           4
        .value_kind:     hidden_block_count_x
      - .offset:         268
        .size:           4
        .value_kind:     hidden_block_count_y
      - .offset:         272
        .size:           4
        .value_kind:     hidden_block_count_z
      - .offset:         276
        .size:           2
        .value_kind:     hidden_group_size_x
      - .offset:         278
        .size:           2
        .value_kind:     hidden_group_size_y
      - .offset:         280
        .size:           2
        .value_kind:     hidden_group_size_z
      - .offset:         282
        .size:           2
        .value_kind:     hidden_remainder_x
      - .offset:         284
        .size:           2
        .value_kind:     hidden_remainder_y
      - .offset:         286
        .size:           2
        .value_kind:     hidden_remainder_z
      - .offset:         304
        .size:           8
        .value_kind:     hidden_global_offset_x
      - .offset:         312
        .size:           8
        .value_kind:     hidden_global_offset_y
      - .offset:         320
        .size:           8
        .value_kind:     hidden_global_offset_z
      - .offset:         328
        .size:           2
        .value_kind:     hidden_grid_dims
      - .offset:         384
        .size:           4
        .value_kind:     hidden_dynamic_lds_size
    .group_segment_fixed_size: 0
    .kernarg_segment_align: 8
    .kernarg_segment_size: 520
    .language:       OpenCL C
    .language_version:
      - 2
      - 0
    .max_flat_workgroup_size: 512
    .name:           _Z9hymba_fwd6Params
    .private_segment_fixed_size: 0
    .sgpr_count:     106
    .sgpr_spill_count: 95
    .symbol:         _Z9hymba_fwd6Params.kd
    .uniform_work_group_size: 1
    .uses_dynamic_stack: false
    .vgpr_count:     256
    .vgpr_spill_count: 0
    .wavefront_size: 64
